# opt7A: + top-k threshold search early exit when count equals k (identical selection)
# speedup vs baseline: 1.0385x; 1.0020x over previous
; __device__ __forceinline__ void a_unit(const ACtx& X, int b, int t0, float* ldsw, int lane) {
;     ...
;         for (int i = 0; i < 4; ++i) { const int j = lane + 64 * i; const float v = (j == 0 || j == cur || j == cur - 1) ? 1e4f : fmaxf(impL[qi * 256 + j], 0.f); key[i] = (j > cur) ? 0u : (__float_as_uint(v) + 1u); }
;         unsigned T = 0u;
;     ...
;             const unsigned cand = T | (1u << bit);
;             int cge = 0;
; #pragma unroll
;             for (int i = 0; i < 4; ++i) cge += __popcll(__ballot(key[i] >= cand));
;             if (cge >= cnt) T = cand;
;         }
;         int ngt = 0;
; #pragma unroll
;         for (int i = 0; i < 4; ++i) ngt += __popcll(__ballot(key[i] > T));
;         int need = cnt - ngt, base = 0;
; #pragma unroll
;         for (int i = 0; i < 4; ++i) {
;             const unsigned long long Me = __ballot(key[i] == T);
;             const int pos = base + (int)__builtin_amdgcn_mbcnt_hi((unsigned)(Me >> 32), __builtin_amdgcn_mbcnt_lo((unsigned)Me, 0u));
;             const bool sel = (key[i] > T) || (key[i] == T && pos < need);
;             const unsigned long long Ms = __ballot(sel);
;             if (lane == 0) { qbits[qi * 8 + 2 * i] = (unsigned)Ms; qbits[qi * 8 + 2 * i + 1] = (unsigned)(Ms >> 32); }
;             base += __popcll(Me);
;         }
.LBB0_720:
	s_or_b64 exec, exec, s[2:3]
	v_cmp_lt_u32_e32 vcc, s14, v196
	v_cmp_lt_u32_e64 s[10:11], s14, v195
	v_cmp_lt_u32_e64 s[12:13], s14, v167
	s_min_u32 s38, s14, 15
	v_cmp_lt_u32_e64 s[14:15], s14, v197
	s_mov_b32 s33, 0
	v_cndmask_b32_e64 v3, v3, 0, vcc
	v_cndmask_b32_e64 v4, v4, 0, s[10:11]
	v_cndmask_b32_e64 v5, v2, 0, s[12:13]
	v_cndmask_b32_e64 v2, v6, 0, s[14:15]
	s_mov_b32 s2, 30
	s_add_i32 s100, s38, 1
.LBB0_721:
	s_lshl_b32 s3, 1, s2
	s_or_b32 s3, s3, s33
	v_cmp_le_u32_e64 s[16:17], s3, v5
	s_bcnt1_i32_b64 s18, s[16:17]
	v_cmp_le_u32_e64 s[16:17], s3, v4
	s_bcnt1_i32_b64 s16, s[16:17]
	s_add_i32 s18, s16, s18
	v_cmp_le_u32_e64 s[16:17], s3, v3
	s_bcnt1_i32_b64 s16, s[16:17]
	s_add_i32 s18, s18, s16
	v_cmp_le_u32_e64 s[16:17], s3, v2
	s_bcnt1_i32_b64 s16, s[16:17]
	s_add_i32 s18, s18, s16
	s_cmp_eq_u32 s18, s100
	s_cbranch_scc1 .Ltk_exit_0
	s_cmp_gt_u32 s18, s38
	s_cselect_b32 s33, s3, s33
	s_add_i32 s2, s2, -1
	s_cmp_eq_u32 s2, -1
	s_cbranch_scc0 .LBB0_721
.Ltk_cont_0:
	v_cmp_lt_u32_e64 s[16:17], s33, v5
	s_bcnt1_i32_b64 s2, s[16:17]
	v_cmp_lt_u32_e64 s[16:17], s33, v4
	s_bcnt1_i32_b64 s3, s[16:17]
	v_cmp_lt_u32_e64 s[16:17], s33, v3
	s_bcnt1_i32_b64 s36, s[16:17]
	v_cmp_lt_u32_e64 s[22:23], s33, v2
	s_add_i32 s2, s2, s3
	s_bcnt1_i32_b64 s22, s[22:23]
	s_add_i32 s2, s2, s36
	s_add_i32 s39, s38, 1
	s_add_i32 s2, s2, s22
	v_cmp_ge_u32_e64 s[24:25], s33, v5
	v_cmp_ge_u32_e64 s[20:21], s33, v4
	v_cmp_ge_u32_e64 s[18:19], s33, v3
	v_cmp_ge_u32_e64 s[16:17], s33, v2
	s_sub_i32 s40, s39, s2
	v_cmp_eq_u32_e64 s[22:23], s33, v5
	s_mov_b64 s[36:37], -1
	s_and_saveexec_b64 s[2:3], s[24:25]
	v_mbcnt_lo_u32_b32 v5, s22, 0
	v_mbcnt_hi_u32_b32 v5, s23, v5
	v_cmp_gt_i32_e64 s[24:25], s40, v5
	s_and_b64 s[24:25], s[22:23], s[24:25]
	s_orn2_b64 s[36:37], s[24:25], exec
	s_or_b64 exec, exec, s[2:3]
	v_cndmask_b32_e64 v5, 0, 1, s[36:37]
	v_cmp_ne_u32_e64 s[24:25], 0, v5
	s_and_saveexec_b64 s[2:3], s[8:9]
	v_mov_b32_e32 v5, s92
	v_mov_b64_e32 v[6:7], s[24:25]
	ds_write_b64 v5, v[6:7] offset:16896
	s_or_b64 exec, exec, s[2:3]
	s_bcnt1_i32_b64 s36, s[22:23]
	v_cmp_eq_u32_e64 s[22:23], s33, v4
	s_mov_b64 s[24:25], -1
	s_and_saveexec_b64 s[2:3], s[20:21]
	v_mbcnt_lo_u32_b32 v4, s22, 0
	v_mbcnt_hi_u32_b32 v4, s23, v4
	v_add_u32_e32 v4, s36, v4
	v_cmp_gt_i32_e64 s[20:21], s40, v4
	s_and_b64 s[20:21], s[22:23], s[20:21]
	s_orn2_b64 s[24:25], s[20:21], exec
	s_or_b64 exec, exec, s[2:3]
	v_cndmask_b32_e64 v4, 0, 1, s[24:25]
	v_cmp_ne_u32_e64 s[20:21], 0, v4
	s_and_saveexec_b64 s[2:3], s[8:9]
	v_mov_b32_e32 v4, s92
	v_mov_b64_e32 v[6:7], s[20:21]
	ds_write_b64 v4, v[6:7] offset:16904
	s_or_b64 exec, exec, s[2:3]
	s_bcnt1_i32_b64 s24, s[22:23]
	s_add_i32 s24, s24, s36
	v_cmp_eq_u32_e64 s[20:21], s33, v3
	s_mov_b64 s[22:23], -1
	s_and_saveexec_b64 s[2:3], s[18:19]
	v_mbcnt_lo_u32_b32 v3, s20, 0
	v_mbcnt_hi_u32_b32 v3, s21, v3
	v_add_u32_e32 v3, s24, v3
	v_cmp_gt_i32_e64 s[18:19], s40, v3
	s_and_b64 s[18:19], s[20:21], s[18:19]
	s_orn2_b64 s[22:23], s[18:19], exec
	s_or_b64 exec, exec, s[2:3]
	v_cndmask_b32_e64 v3, 0, 1, s[22:23]
	v_cmp_ne_u32_e64 s[18:19], 0, v3
	s_and_saveexec_b64 s[2:3], s[8:9]
	v_mov_b32_e32 v3, s92
	v_mov_b64_e32 v[4:5], s[18:19]
	ds_write_b64 v3, v[4:5] offset:16912
	s_or_b64 exec, exec, s[2:3]
	v_cmp_eq_u32_e64 s[18:19], s33, v2
	s_mov_b64 s[22:23], -1
	s_and_saveexec_b64 s[2:3], s[16:17]
	s_bcnt1_i32_b64 s16, s[20:21]
	v_mbcnt_lo_u32_b32 v2, s18, 0
	s_add_i32 s24, s24, s16
	v_mbcnt_hi_u32_b32 v2, s19, v2
	v_add_u32_e32 v2, s24, v2
	v_cmp_gt_i32_e64 s[16:17], s40, v2
	s_and_b64 s[16:17], s[18:19], s[16:17]
	s_orn2_b64 s[22:23], s[16:17], exec
	s_or_b64 exec, exec, s[2:3]
	v_cndmask_b32_e64 v2, 0, 1, s[22:23]
	v_cmp_ne_u32_e64 s[16:17], 0, v2
	s_and_saveexec_b64 s[2:3], s[8:9]
	v_mov_b32_e32 v2, s92
	v_mov_b64_e32 v[4:5], s[16:17]
	ds_write_b64 v2, v[4:5] offset:16920
	s_or_b64 exec, exec, s[2:3]
	v_mov_b32_e32 v4, 0x461c4001
	v_mov_b32_e32 v2, 0x461c4001
	s_and_saveexec_b64 s[2:3], s[26:27]
	s_cbranch_execz .LBB0_740
	ds_read_b32 v2, v191 offset:9728
	s_waitcnt lgkmcnt(0)
	v_max_f32_e32 v2, v2, v2
	v_max_f32_e32 v2, 0, v2
	v_add_u32_e32 v2, 1, v2

; __device__ __forceinline__ void a_unit(const ACtx& X, int b, int t0, float* ldsw, int lane) {
;     ...
;         for (int i = 0; i < 4; ++i) { const int j = lane + 64 * i; const float v = (j == 0 || j == cur || j == cur - 1) ? 1e4f : fmaxf(impL[qi * 256 + j], 0.f); key[i] = (j > cur) ? 0u : (__float_as_uint(v) + 1u); }
;         unsigned T = 0u;
;     ...
;             const unsigned cand = T | (1u << bit);
;             int cge = 0;
; #pragma unroll
;             for (int i = 0; i < 4; ++i) cge += __popcll(__ballot(key[i] >= cand));
;             if (cge >= cnt) T = cand;
;         }
;         int ngt = 0;
; #pragma unroll
;         for (int i = 0; i < 4; ++i) ngt += __popcll(__ballot(key[i] > T));
;         int need = cnt - ngt, base = 0;
; #pragma unroll
;         for (int i = 0; i < 4; ++i) {
;             const unsigned long long Me = __ballot(key[i] == T);
;             const int pos = base + (int)__builtin_amdgcn_mbcnt_hi((unsigned)(Me >> 32), __builtin_amdgcn_mbcnt_lo((unsigned)Me, 0u));
;             const bool sel = (key[i] > T) || (key[i] == T && pos < need);
;             const unsigned long long Ms = __ballot(sel);
;             if (lane == 0) { qbits[qi * 8 + 2 * i] = (unsigned)Ms; qbits[qi * 8 + 2 * i + 1] = (unsigned)(Ms >> 32); }
;             base += __popcll(Me);
;         }
.LBB0_746:
	s_or_b64 exec, exec, s[2:3]
	s_mov_b32 s33, 0
	v_cndmask_b32_e64 v3, v3, 0, vcc
	v_cndmask_b32_e64 v4, v4, 0, s[10:11]
	v_cndmask_b32_e64 v5, v2, 0, s[12:13]
	v_cndmask_b32_e64 v2, v6, 0, s[14:15]
	s_mov_b32 s2, 30
	s_add_i32 s100, s38, 1
.LBB0_747:
	s_lshl_b32 s3, 1, s2
	s_or_b32 s3, s3, s33
	v_cmp_le_u32_e64 s[16:17], s3, v5
	s_bcnt1_i32_b64 s18, s[16:17]
	v_cmp_le_u32_e64 s[16:17], s3, v4
	s_bcnt1_i32_b64 s16, s[16:17]
	s_add_i32 s18, s16, s18
	v_cmp_le_u32_e64 s[16:17], s3, v3
	s_bcnt1_i32_b64 s16, s[16:17]
	s_add_i32 s18, s18, s16
	v_cmp_le_u32_e64 s[16:17], s3, v2
	s_bcnt1_i32_b64 s16, s[16:17]
	s_add_i32 s18, s18, s16
	s_cmp_eq_u32 s18, s100
	s_cbranch_scc1 .Ltk_exit_1
	s_cmp_gt_u32 s18, s38
	s_cselect_b32 s33, s3, s33
	s_add_i32 s2, s2, -1
	s_cmp_lg_u32 s2, -1
	s_cbranch_scc1 .LBB0_747
.Ltk_cont_1:
	v_cmp_lt_u32_e64 s[16:17], s33, v5
	s_bcnt1_i32_b64 s2, s[16:17]
	v_cmp_lt_u32_e64 s[16:17], s33, v4
	s_bcnt1_i32_b64 s3, s[16:17]
	v_cmp_lt_u32_e64 s[16:17], s33, v3
	s_bcnt1_i32_b64 s36, s[16:17]
	v_cmp_lt_u32_e64 s[22:23], s33, v2
	s_add_i32 s2, s2, s3
	s_bcnt1_i32_b64 s22, s[22:23]
	s_add_i32 s2, s2, s36
	s_add_i32 s2, s2, s22
	v_cmp_ge_u32_e64 s[24:25], s33, v5
	v_cmp_ge_u32_e64 s[20:21], s33, v4
	v_cmp_ge_u32_e64 s[18:19], s33, v3
	v_cmp_ge_u32_e64 s[16:17], s33, v2
	s_sub_i32 s40, s39, s2
	v_cmp_eq_u32_e64 s[22:23], s33, v5
	s_mov_b64 s[36:37], -1
	s_and_saveexec_b64 s[2:3], s[24:25]
	v_mbcnt_lo_u32_b32 v5, s22, 0
	v_mbcnt_hi_u32_b32 v5, s23, v5
	v_cmp_gt_i32_e64 s[24:25], s40, v5
	s_and_b64 s[24:25], s[22:23], s[24:25]
	s_orn2_b64 s[36:37], s[24:25], exec
	s_or_b64 exec, exec, s[2:3]
	v_cndmask_b32_e64 v5, 0, 1, s[36:37]
	v_cmp_ne_u32_e64 s[24:25], 0, v5
	s_and_saveexec_b64 s[2:3], s[8:9]
	v_mov_b32_e32 v5, s92
	v_mov_b64_e32 v[6:7], s[24:25]
	ds_write_b64 v5, v[6:7] offset:16928
	s_or_b64 exec, exec, s[2:3]
	s_bcnt1_i32_b64 s36, s[22:23]
	v_cmp_eq_u32_e64 s[22:23], s33, v4
	s_mov_b64 s[24:25], -1
	s_and_saveexec_b64 s[2:3], s[20:21]
	v_mbcnt_lo_u32_b32 v4, s22, 0
	v_mbcnt_hi_u32_b32 v4, s23, v4
	v_add_u32_e32 v4, s36, v4
	v_cmp_gt_i32_e64 s[20:21], s40, v4
	s_and_b64 s[20:21], s[22:23], s[20:21]
	s_orn2_b64 s[24:25], s[20:21], exec
	s_or_b64 exec, exec, s[2:3]
	v_cndmask_b32_e64 v4, 0, 1, s[24:25]
	v_cmp_ne_u32_e64 s[20:21], 0, v4
	s_and_saveexec_b64 s[2:3], s[8:9]
	v_mov_b32_e32 v4, s92
	v_mov_b64_e32 v[6:7], s[20:21]
	ds_write_b64 v4, v[6:7] offset:16936
	s_or_b64 exec, exec, s[2:3]
	s_bcnt1_i32_b64 s24, s[22:23]
	s_add_i32 s24, s24, s36
	v_cmp_eq_u32_e64 s[20:21], s33, v3
	s_mov_b64 s[22:23], -1
	s_and_saveexec_b64 s[2:3], s[18:19]
	v_mbcnt_lo_u32_b32 v3, s20, 0
	v_mbcnt_hi_u32_b32 v3, s21, v3
	v_add_u32_e32 v3, s24, v3
	v_cmp_gt_i32_e64 s[18:19], s40, v3
	s_and_b64 s[18:19], s[20:21], s[18:19]
	s_orn2_b64 s[22:23], s[18:19], exec
	s_or_b64 exec, exec, s[2:3]
	v_cndmask_b32_e64 v3, 0, 1, s[22:23]
	v_cmp_ne_u32_e64 s[18:19], 0, v3
	s_and_saveexec_b64 s[2:3], s[8:9]
	v_mov_b32_e32 v3, s92
	v_mov_b64_e32 v[4:5], s[18:19]
	ds_write_b64 v3, v[4:5] offset:16944
	s_or_b64 exec, exec, s[2:3]
	v_cmp_eq_u32_e64 s[18:19], s33, v2
	s_mov_b64 s[22:23], -1
	s_and_saveexec_b64 s[2:3], s[16:17]
	s_bcnt1_i32_b64 s16, s[20:21]
	v_mbcnt_lo_u32_b32 v2, s18, 0
	s_add_i32 s24, s24, s16
	v_mbcnt_hi_u32_b32 v2, s19, v2
	v_add_u32_e32 v2, s24, v2
	v_cmp_gt_i32_e64 s[16:17], s40, v2
	s_and_b64 s[16:17], s[18:19], s[16:17]
	s_orn2_b64 s[22:23], s[16:17], exec
	s_or_b64 exec, exec, s[2:3]
	v_cndmask_b32_e64 v2, 0, 1, s[22:23]
	v_cmp_ne_u32_e64 s[16:17], 0, v2
	s_and_saveexec_b64 s[2:3], s[8:9]
	v_mov_b32_e32 v2, s92
	v_mov_b64_e32 v[4:5], s[16:17]
	ds_write_b64 v2, v[4:5] offset:16952
	s_or_b64 exec, exec, s[2:3]
	v_mov_b32_e32 v4, 0x461c4001
	v_mov_b32_e32 v2, 0x461c4001
	s_and_saveexec_b64 s[2:3], s[26:27]
	s_cbranch_execz .LBB0_766
	ds_read_b32 v2, v191 offset:10752
	s_waitcnt lgkmcnt(0)
	v_max_f32_e32 v2, v2, v2
	v_max_f32_e32 v2, 0, v2
	v_add_u32_e32 v2, 1, v2

; __device__ __forceinline__ void a_unit(const ACtx& X, int b, int t0, float* ldsw, int lane) {
;     ...
;         for (int i = 0; i < 4; ++i) { const int j = lane + 64 * i; const float v = (j == 0 || j == cur || j == cur - 1) ? 1e4f : fmaxf(impL[qi * 256 + j], 0.f); key[i] = (j > cur) ? 0u : (__float_as_uint(v) + 1u); }
;         unsigned T = 0u;
;     ...
;             const unsigned cand = T | (1u << bit);
;             int cge = 0;
; #pragma unroll
;             for (int i = 0; i < 4; ++i) cge += __popcll(__ballot(key[i] >= cand));
;             if (cge >= cnt) T = cand;
;         }
;         int ngt = 0;
; #pragma unroll
;         for (int i = 0; i < 4; ++i) ngt += __popcll(__ballot(key[i] > T));
;         int need = cnt - ngt, base = 0;
; #pragma unroll
;         for (int i = 0; i < 4; ++i) {
;             const unsigned long long Me = __ballot(key[i] == T);
;             const int pos = base + (int)__builtin_amdgcn_mbcnt_hi((unsigned)(Me >> 32), __builtin_amdgcn_mbcnt_lo((unsigned)Me, 0u));
;             const bool sel = (key[i] > T) || (key[i] == T && pos < need);
;             const unsigned long long Ms = __ballot(sel);
;             if (lane == 0) { qbits[qi * 8 + 2 * i] = (unsigned)Ms; qbits[qi * 8 + 2 * i + 1] = (unsigned)(Ms >> 32); }
;             base += __popcll(Me);
;         }
.Ltk_cont_2:
	v_cmp_lt_u32_e64 s[16:17], s33, v5
	s_bcnt1_i32_b64 s2, s[16:17]
	v_cmp_lt_u32_e64 s[16:17], s33, v4
	s_bcnt1_i32_b64 s3, s[16:17]
	v_cmp_lt_u32_e64 s[16:17], s33, v3
	s_bcnt1_i32_b64 s36, s[16:17]
	v_cmp_lt_u32_e64 s[22:23], s33, v2
	s_add_i32 s2, s2, s3
	s_bcnt1_i32_b64 s22, s[22:23]
	s_add_i32 s2, s2, s36
	s_add_i32 s2, s2, s22
	v_cmp_ge_u32_e64 s[24:25], s33, v5
	v_cmp_ge_u32_e64 s[20:21], s33, v4
	v_cmp_ge_u32_e64 s[18:19], s33, v3
	v_cmp_ge_u32_e64 s[16:17], s33, v2
	s_sub_i32 s40, s39, s2
	v_cmp_eq_u32_e64 s[22:23], s33, v5
	s_mov_b64 s[36:37], -1
	s_and_saveexec_b64 s[2:3], s[24:25]
	v_mbcnt_lo_u32_b32 v5, s22, 0
	v_mbcnt_hi_u32_b32 v5, s23, v5
	v_cmp_gt_i32_e64 s[24:25], s40, v5
	s_and_b64 s[24:25], s[22:23], s[24:25]
	s_orn2_b64 s[36:37], s[24:25], exec
	s_or_b64 exec, exec, s[2:3]
	v_cndmask_b32_e64 v5, 0, 1, s[36:37]
	v_cmp_ne_u32_e64 s[24:25], 0, v5
	s_and_saveexec_b64 s[2:3], s[8:9]
	v_mov_b32_e32 v5, s92
	v_mov_b64_e32 v[6:7], s[24:25]
	ds_write_b64 v5, v[6:7] offset:16960
	s_or_b64 exec, exec, s[2:3]
	s_bcnt1_i32_b64 s36, s[22:23]
	v_cmp_eq_u32_e64 s[22:23], s33, v4
	s_mov_b64 s[24:25], -1
	s_and_saveexec_b64 s[2:3], s[20:21]
	v_mbcnt_lo_u32_b32 v4, s22, 0
	v_mbcnt_hi_u32_b32 v4, s23, v4
	v_add_u32_e32 v4, s36, v4
	v_cmp_gt_i32_e64 s[20:21], s40, v4
	s_and_b64 s[20:21], s[22:23], s[20:21]
	s_orn2_b64 s[24:25], s[20:21], exec
	s_or_b64 exec, exec, s[2:3]
	v_cndmask_b32_e64 v4, 0, 1, s[24:25]
	v_cmp_ne_u32_e64 s[20:21], 0, v4
	s_and_saveexec_b64 s[2:3], s[8:9]
	v_mov_b32_e32 v4, s92
	v_mov_b64_e32 v[6:7], s[20:21]
	ds_write_b64 v4, v[6:7] offset:16968
	s_or_b64 exec, exec, s[2:3]
	s_bcnt1_i32_b64 s24, s[22:23]
	s_add_i32 s24, s24, s36
	v_cmp_eq_u32_e64 s[20:21], s33, v3
	s_mov_b64 s[22:23], -1
	s_and_saveexec_b64 s[2:3], s[18:19]
	v_mbcnt_lo_u32_b32 v3, s20, 0
	v_mbcnt_hi_u32_b32 v3, s21, v3
	v_add_u32_e32 v3, s24, v3
	v_cmp_gt_i32_e64 s[18:19], s40, v3
	s_and_b64 s[18:19], s[20:21], s[18:19]
	s_orn2_b64 s[22:23], s[18:19], exec
	s_or_b64 exec, exec, s[2:3]
	v_cndmask_b32_e64 v3, 0, 1, s[22:23]
	v_cmp_ne_u32_e64 s[18:19], 0, v3
	s_and_saveexec_b64 s[2:3], s[8:9]
	v_mov_b32_e32 v3, s92
	v_mov_b64_e32 v[4:5], s[18:19]
	ds_write_b64 v3, v[4:5] offset:16976
	s_or_b64 exec, exec, s[2:3]
	v_cmp_eq_u32_e64 s[18:19], s33, v2
	s_mov_b64 s[22:23], -1
	s_and_saveexec_b64 s[2:3], s[16:17]
	s_bcnt1_i32_b64 s16, s[20:21]
	v_mbcnt_lo_u32_b32 v2, s18, 0
	s_add_i32 s24, s24, s16
	v_mbcnt_hi_u32_b32 v2, s19, v2
	v_add_u32_e32 v2, s24, v2
	v_cmp_gt_i32_e64 s[16:17], s40, v2
	s_and_b64 s[16:17], s[18:19], s[16:17]
	s_orn2_b64 s[22:23], s[16:17], exec
	s_or_b64 exec, exec, s[2:3]
	v_cndmask_b32_e64 v2, 0, 1, s[22:23]
	v_cmp_ne_u32_e64 s[16:17], 0, v2
	s_and_saveexec_b64 s[2:3], s[8:9]
	v_mov_b32_e32 v2, s92
	v_mov_b64_e32 v[4:5], s[16:17]
	ds_write_b64 v2, v[4:5] offset:16984
	s_or_b64 exec, exec, s[2:3]
	v_mov_b32_e32 v4, 0x461c4001
	v_mov_b32_e32 v2, 0x461c4001
	s_and_saveexec_b64 s[2:3], s[26:27]
	s_cbranch_execz .LBB0_792
	ds_read_b32 v2, v191 offset:11776
	s_waitcnt lgkmcnt(0)
	v_max_f32_e32 v2, v2, v2
	v_max_f32_e32 v2, 0, v2
	v_add_u32_e32 v2, 1, v2

; __device__ __forceinline__ void a_unit(const ACtx& X, int b, int t0, float* ldsw, int lane) {
;     ...
;         for (int i = 0; i < 4; ++i) { const int j = lane + 64 * i; const float v = (j == 0 || j == cur || j == cur - 1) ? 1e4f : fmaxf(impL[qi * 256 + j], 0.f); key[i] = (j > cur) ? 0u : (__float_as_uint(v) + 1u); }
;         unsigned T = 0u;
;     ...
;             const unsigned cand = T | (1u << bit);
;             int cge = 0;
; #pragma unroll
;             for (int i = 0; i < 4; ++i) cge += __popcll(__ballot(key[i] >= cand));
;             if (cge >= cnt) T = cand;
;         }
;         int ngt = 0;
; #pragma unroll
;         for (int i = 0; i < 4; ++i) ngt += __popcll(__ballot(key[i] > T));
;         int need = cnt - ngt, base = 0;
; #pragma unroll
;         for (int i = 0; i < 4; ++i) {
;             const unsigned long long Me = __ballot(key[i] == T);
;             const int pos = base + (int)__builtin_amdgcn_mbcnt_hi((unsigned)(Me >> 32), __builtin_amdgcn_mbcnt_lo((unsigned)Me, 0u));
;             const bool sel = (key[i] > T) || (key[i] == T && pos < need);
;             const unsigned long long Ms = __ballot(sel);
;             if (lane == 0) { qbits[qi * 8 + 2 * i] = (unsigned)Ms; qbits[qi * 8 + 2 * i + 1] = (unsigned)(Ms >> 32); }
;             base += __popcll(Me);
;         }
.Ltk_cont_3:
	v_cmp_lt_u32_e64 s[16:17], s33, v5
	s_bcnt1_i32_b64 s2, s[16:17]
	v_cmp_lt_u32_e64 s[16:17], s33, v4
	s_bcnt1_i32_b64 s3, s[16:17]
	v_cmp_lt_u32_e64 s[16:17], s33, v3
	s_bcnt1_i32_b64 s36, s[16:17]
	v_cmp_lt_u32_e64 s[22:23], s33, v2
	s_add_i32 s2, s2, s3
	s_bcnt1_i32_b64 s22, s[22:23]
	s_add_i32 s2, s2, s36
	s_add_i32 s2, s2, s22
	v_cmp_ge_u32_e64 s[24:25], s33, v5
	v_cmp_ge_u32_e64 s[20:21], s33, v4
	v_cmp_ge_u32_e64 s[18:19], s33, v3
	v_cmp_ge_u32_e64 s[16:17], s33, v2
	s_sub_i32 s40, s39, s2
	v_cmp_eq_u32_e64 s[22:23], s33, v5
	s_mov_b64 s[36:37], -1
	s_and_saveexec_b64 s[2:3], s[24:25]
	v_mbcnt_lo_u32_b32 v5, s22, 0
	v_mbcnt_hi_u32_b32 v5, s23, v5
	v_cmp_gt_i32_e64 s[24:25], s40, v5
	s_and_b64 s[24:25], s[22:23], s[24:25]
	s_orn2_b64 s[36:37], s[24:25], exec
	s_or_b64 exec, exec, s[2:3]
	v_cndmask_b32_e64 v5, 0, 1, s[36:37]
	v_cmp_ne_u32_e64 s[24:25], 0, v5
	s_and_saveexec_b64 s[2:3], s[8:9]
	v_mov_b32_e32 v5, s92
	v_mov_b64_e32 v[6:7], s[24:25]
	ds_write_b64 v5, v[6:7] offset:16992
	s_or_b64 exec, exec, s[2:3]
	s_bcnt1_i32_b64 s36, s[22:23]
	v_cmp_eq_u32_e64 s[22:23], s33, v4
	s_mov_b64 s[24:25], -1
	s_and_saveexec_b64 s[2:3], s[20:21]
	v_mbcnt_lo_u32_b32 v4, s22, 0
	v_mbcnt_hi_u32_b32 v4, s23, v4
	v_add_u32_e32 v4, s36, v4
	v_cmp_gt_i32_e64 s[20:21], s40, v4
	s_and_b64 s[20:21], s[22:23], s[20:21]
	s_orn2_b64 s[24:25], s[20:21], exec
	s_or_b64 exec, exec, s[2:3]
	v_cndmask_b32_e64 v4, 0, 1, s[24:25]
	v_cmp_ne_u32_e64 s[20:21], 0, v4
	s_and_saveexec_b64 s[2:3], s[8:9]
	v_mov_b32_e32 v4, s92
	v_mov_b64_e32 v[6:7], s[20:21]
	ds_write_b64 v4, v[6:7] offset:17000
	s_or_b64 exec, exec, s[2:3]
	s_bcnt1_i32_b64 s24, s[22:23]
	s_add_i32 s24, s24, s36
	v_cmp_eq_u32_e64 s[20:21], s33, v3
	s_mov_b64 s[22:23], -1
	s_and_saveexec_b64 s[2:3], s[18:19]
	v_mbcnt_lo_u32_b32 v3, s20, 0
	v_mbcnt_hi_u32_b32 v3, s21, v3
	v_add_u32_e32 v3, s24, v3
	v_cmp_gt_i32_e64 s[18:19], s40, v3
	s_and_b64 s[18:19], s[20:21], s[18:19]
	s_orn2_b64 s[22:23], s[18:19], exec
	s_or_b64 exec, exec, s[2:3]
	v_cndmask_b32_e64 v3, 0, 1, s[22:23]
	v_cmp_ne_u32_e64 s[18:19], 0, v3
	s_and_saveexec_b64 s[2:3], s[8:9]
	v_mov_b32_e32 v3, s92
	v_mov_b64_e32 v[4:5], s[18:19]
	ds_write_b64 v3, v[4:5] offset:17008
	s_or_b64 exec, exec, s[2:3]
	v_cmp_eq_u32_e64 s[18:19], s33, v2
	s_mov_b64 s[22:23], -1
	s_and_saveexec_b64 s[2:3], s[16:17]
	s_bcnt1_i32_b64 s16, s[20:21]
	v_mbcnt_lo_u32_b32 v2, s18, 0
	s_add_i32 s24, s24, s16
	v_mbcnt_hi_u32_b32 v2, s19, v2
	v_add_u32_e32 v2, s24, v2
	v_cmp_gt_i32_e64 s[16:17], s40, v2
	s_and_b64 s[16:17], s[18:19], s[16:17]
	s_orn2_b64 s[22:23], s[16:17], exec
	s_or_b64 exec, exec, s[2:3]
	v_cndmask_b32_e64 v2, 0, 1, s[22:23]
	v_cmp_ne_u32_e64 s[16:17], 0, v2
	s_and_saveexec_b64 s[2:3], s[8:9]
	v_mov_b32_e32 v2, s92
	v_mov_b64_e32 v[4:5], s[16:17]
	ds_write_b64 v2, v[4:5] offset:17016
	s_or_b64 exec, exec, s[2:3]
	v_mov_b32_e32 v4, 0x461c4001
	v_mov_b32_e32 v2, 0x461c4001
	s_and_saveexec_b64 s[2:3], s[26:27]
	s_cbranch_execz .LBB0_818
	ds_read_b32 v2, v191 offset:12800
	s_waitcnt lgkmcnt(0)
	v_max_f32_e32 v2, v2, v2
	v_max_f32_e32 v2, 0, v2
	v_add_u32_e32 v2, 1, v2

; __device__ __forceinline__ void a_unit(const ACtx& X, int b, int t0, float* ldsw, int lane) {
;     ...
;         for (int i = 0; i < 4; ++i) { const int j = lane + 64 * i; const float v = (j == 0 || j == cur || j == cur - 1) ? 1e4f : fmaxf(impL[qi * 256 + j], 0.f); key[i] = (j > cur) ? 0u : (__float_as_uint(v) + 1u); }
;         unsigned T = 0u;
;     ...
;             const unsigned cand = T | (1u << bit);
;             int cge = 0;
; #pragma unroll
;             for (int i = 0; i < 4; ++i) cge += __popcll(__ballot(key[i] >= cand));
;             if (cge >= cnt) T = cand;
;         }
;         int ngt = 0;
; #pragma unroll
;         for (int i = 0; i < 4; ++i) ngt += __popcll(__ballot(key[i] > T));
;         int need = cnt - ngt, base = 0;
; #pragma unroll
;         for (int i = 0; i < 4; ++i) {
;             const unsigned long long Me = __ballot(key[i] == T);
;             const int pos = base + (int)__builtin_amdgcn_mbcnt_hi((unsigned)(Me >> 32), __builtin_amdgcn_mbcnt_lo((unsigned)Me, 0u));
;             const bool sel = (key[i] > T) || (key[i] == T && pos < need);
;             const unsigned long long Ms = __ballot(sel);
;             if (lane == 0) { qbits[qi * 8 + 2 * i] = (unsigned)Ms; qbits[qi * 8 + 2 * i + 1] = (unsigned)(Ms >> 32); }
;             base += __popcll(Me);
;         }
.Ltk_cont_4:
	v_cmp_lt_u32_e64 s[16:17], s33, v5
	s_bcnt1_i32_b64 s2, s[16:17]
	v_cmp_lt_u32_e64 s[16:17], s33, v4
	s_bcnt1_i32_b64 s3, s[16:17]
	v_cmp_lt_u32_e64 s[16:17], s33, v3
	s_bcnt1_i32_b64 s36, s[16:17]
	v_cmp_lt_u32_e64 s[22:23], s33, v2
	s_add_i32 s2, s2, s3
	s_bcnt1_i32_b64 s22, s[22:23]
	s_add_i32 s2, s2, s36
	s_add_i32 s2, s2, s22
	v_cmp_ge_u32_e64 s[24:25], s33, v5
	v_cmp_ge_u32_e64 s[20:21], s33, v4
	v_cmp_ge_u32_e64 s[18:19], s33, v3
	v_cmp_ge_u32_e64 s[16:17], s33, v2
	s_sub_i32 s40, s39, s2
	v_cmp_eq_u32_e64 s[22:23], s33, v5
	s_mov_b64 s[36:37], -1
	s_and_saveexec_b64 s[2:3], s[24:25]
	v_mbcnt_lo_u32_b32 v5, s22, 0
	v_mbcnt_hi_u32_b32 v5, s23, v5
	v_cmp_gt_i32_e64 s[24:25], s40, v5
	s_and_b64 s[24:25], s[22:23], s[24:25]
	s_orn2_b64 s[36:37], s[24:25], exec
	s_or_b64 exec, exec, s[2:3]
	v_cndmask_b32_e64 v5, 0, 1, s[36:37]
	v_cmp_ne_u32_e64 s[24:25], 0, v5
	s_and_saveexec_b64 s[2:3], s[8:9]
	v_mov_b32_e32 v5, s92
	v_mov_b64_e32 v[6:7], s[24:25]
	ds_write_b64 v5, v[6:7] offset:17024
	s_or_b64 exec, exec, s[2:3]
	s_bcnt1_i32_b64 s36, s[22:23]
	v_cmp_eq_u32_e64 s[22:23], s33, v4
	s_mov_b64 s[24:25], -1
	s_and_saveexec_b64 s[2:3], s[20:21]
	v_mbcnt_lo_u32_b32 v4, s22, 0
	v_mbcnt_hi_u32_b32 v4, s23, v4
	v_add_u32_e32 v4, s36, v4
	v_cmp_gt_i32_e64 s[20:21], s40, v4
	s_and_b64 s[20:21], s[22:23], s[20:21]
	s_orn2_b64 s[24:25], s[20:21], exec
	s_or_b64 exec, exec, s[2:3]
	v_cndmask_b32_e64 v4, 0, 1, s[24:25]
	v_cmp_ne_u32_e64 s[20:21], 0, v4
	s_and_saveexec_b64 s[2:3], s[8:9]
	v_mov_b32_e32 v4, s92
	v_mov_b64_e32 v[6:7], s[20:21]
	ds_write_b64 v4, v[6:7] offset:17032
	s_or_b64 exec, exec, s[2:3]
	s_bcnt1_i32_b64 s24, s[22:23]
	s_add_i32 s24, s24, s36
	v_cmp_eq_u32_e64 s[20:21], s33, v3
	s_mov_b64 s[22:23], -1
	s_and_saveexec_b64 s[2:3], s[18:19]
	v_mbcnt_lo_u32_b32 v3, s20, 0
	v_mbcnt_hi_u32_b32 v3, s21, v3
	v_add_u32_e32 v3, s24, v3
	v_cmp_gt_i32_e64 s[18:19], s40, v3
	s_and_b64 s[18:19], s[20:21], s[18:19]
	s_orn2_b64 s[22:23], s[18:19], exec
	s_or_b64 exec, exec, s[2:3]
	v_cndmask_b32_e64 v3, 0, 1, s[22:23]
	v_cmp_ne_u32_e64 s[18:19], 0, v3
	s_and_saveexec_b64 s[2:3], s[8:9]
	v_mov_b32_e32 v3, s92
	v_mov_b64_e32 v[4:5], s[18:19]
	ds_write_b64 v3, v[4:5] offset:17040
	s_or_b64 exec, exec, s[2:3]
	v_cmp_eq_u32_e64 s[18:19], s33, v2
	s_mov_b64 s[22:23], -1
	s_and_saveexec_b64 s[2:3], s[16:17]
	s_bcnt1_i32_b64 s16, s[20:21]
	v_mbcnt_lo_u32_b32 v2, s18, 0
	s_add_i32 s24, s24, s16
	v_mbcnt_hi_u32_b32 v2, s19, v2
	v_add_u32_e32 v2, s24, v2
	v_cmp_gt_i32_e64 s[16:17], s40, v2
	s_and_b64 s[16:17], s[18:19], s[16:17]
	s_orn2_b64 s[22:23], s[16:17], exec
	s_or_b64 exec, exec, s[2:3]
	v_cndmask_b32_e64 v2, 0, 1, s[22:23]
	v_cmp_ne_u32_e64 s[16:17], 0, v2
	s_and_saveexec_b64 s[2:3], s[8:9]
	v_mov_b32_e32 v2, s92
	v_mov_b64_e32 v[4:5], s[16:17]
	ds_write_b64 v2, v[4:5] offset:17048
	s_or_b64 exec, exec, s[2:3]
	v_mov_b32_e32 v4, 0x461c4001
	v_mov_b32_e32 v2, 0x461c4001
	s_and_saveexec_b64 s[2:3], s[26:27]
	s_cbranch_execz .LBB0_844
	ds_read_b32 v2, v191 offset:13824
	s_waitcnt lgkmcnt(0)
	v_max_f32_e32 v2, v2, v2
	v_max_f32_e32 v2, 0, v2
	v_add_u32_e32 v2, 1, v2

; __device__ __forceinline__ void a_unit(const ACtx& X, int b, int t0, float* ldsw, int lane) {
;     ...
;         for (int i = 0; i < 4; ++i) { const int j = lane + 64 * i; const float v = (j == 0 || j == cur || j == cur - 1) ? 1e4f : fmaxf(impL[qi * 256 + j], 0.f); key[i] = (j > cur) ? 0u : (__float_as_uint(v) + 1u); }
;         unsigned T = 0u;
;     ...
;             const unsigned cand = T | (1u << bit);
;             int cge = 0;
; #pragma unroll
;             for (int i = 0; i < 4; ++i) cge += __popcll(__ballot(key[i] >= cand));
;             if (cge >= cnt) T = cand;
;         }
;         int ngt = 0;
; #pragma unroll
;         for (int i = 0; i < 4; ++i) ngt += __popcll(__ballot(key[i] > T));
;         int need = cnt - ngt, base = 0;
; #pragma unroll
;         for (int i = 0; i < 4; ++i) {
;             const unsigned long long Me = __ballot(key[i] == T);
;             const int pos = base + (int)__builtin_amdgcn_mbcnt_hi((unsigned)(Me >> 32), __builtin_amdgcn_mbcnt_lo((unsigned)Me, 0u));
;             const bool sel = (key[i] > T) || (key[i] == T && pos < need);
;             const unsigned long long Ms = __ballot(sel);
;             if (lane == 0) { qbits[qi * 8 + 2 * i] = (unsigned)Ms; qbits[qi * 8 + 2 * i + 1] = (unsigned)(Ms >> 32); }
;             base += __popcll(Me);
;         }
.Ltk_cont_5:
	v_cmp_lt_u32_e64 s[16:17], s33, v5
	s_bcnt1_i32_b64 s2, s[16:17]
	v_cmp_lt_u32_e64 s[16:17], s33, v4
	s_bcnt1_i32_b64 s3, s[16:17]
	v_cmp_lt_u32_e64 s[16:17], s33, v3
	s_bcnt1_i32_b64 s36, s[16:17]
	v_cmp_lt_u32_e64 s[22:23], s33, v2
	s_add_i32 s2, s2, s3
	s_bcnt1_i32_b64 s22, s[22:23]
	s_add_i32 s2, s2, s36
	s_add_i32 s2, s2, s22
	v_cmp_ge_u32_e64 s[24:25], s33, v5
	v_cmp_ge_u32_e64 s[20:21], s33, v4
	v_cmp_ge_u32_e64 s[18:19], s33, v3
	v_cmp_ge_u32_e64 s[16:17], s33, v2
	s_sub_i32 s40, s39, s2
	v_cmp_eq_u32_e64 s[22:23], s33, v5
	s_mov_b64 s[36:37], -1
	s_and_saveexec_b64 s[2:3], s[24:25]
	v_mbcnt_lo_u32_b32 v5, s22, 0
	v_mbcnt_hi_u32_b32 v5, s23, v5
	v_cmp_gt_i32_e64 s[24:25], s40, v5
	s_and_b64 s[24:25], s[22:23], s[24:25]
	s_orn2_b64 s[36:37], s[24:25], exec
	s_or_b64 exec, exec, s[2:3]
	v_cndmask_b32_e64 v5, 0, 1, s[36:37]
	v_cmp_ne_u32_e64 s[24:25], 0, v5
	s_and_saveexec_b64 s[2:3], s[8:9]
	v_mov_b32_e32 v5, s92
	v_mov_b64_e32 v[6:7], s[24:25]
	ds_write_b64 v5, v[6:7] offset:17056
	s_or_b64 exec, exec, s[2:3]
	s_bcnt1_i32_b64 s36, s[22:23]
	v_cmp_eq_u32_e64 s[22:23], s33, v4
	s_mov_b64 s[24:25], -1
	s_and_saveexec_b64 s[2:3], s[20:21]
	v_mbcnt_lo_u32_b32 v4, s22, 0
	v_mbcnt_hi_u32_b32 v4, s23, v4
	v_add_u32_e32 v4, s36, v4
	v_cmp_gt_i32_e64 s[20:21], s40, v4
	s_and_b64 s[20:21], s[22:23], s[20:21]
	s_orn2_b64 s[24:25], s[20:21], exec
	s_or_b64 exec, exec, s[2:3]
	v_cndmask_b32_e64 v4, 0, 1, s[24:25]
	v_cmp_ne_u32_e64 s[20:21], 0, v4
	s_and_saveexec_b64 s[2:3], s[8:9]
	v_mov_b32_e32 v4, s92
	v_mov_b64_e32 v[6:7], s[20:21]
	ds_write_b64 v4, v[6:7] offset:17064
	s_or_b64 exec, exec, s[2:3]
	s_bcnt1_i32_b64 s24, s[22:23]
	s_add_i32 s24, s24, s36
	v_cmp_eq_u32_e64 s[20:21], s33, v3
	s_mov_b64 s[22:23], -1
	s_and_saveexec_b64 s[2:3], s[18:19]
	v_mbcnt_lo_u32_b32 v3, s20, 0
	v_mbcnt_hi_u32_b32 v3, s21, v3
	v_add_u32_e32 v3, s24, v3
	v_cmp_gt_i32_e64 s[18:19], s40, v3
	s_and_b64 s[18:19], s[20:21], s[18:19]
	s_orn2_b64 s[22:23], s[18:19], exec
	s_or_b64 exec, exec, s[2:3]
	v_cndmask_b32_e64 v3, 0, 1, s[22:23]
	v_cmp_ne_u32_e64 s[18:19], 0, v3
	s_and_saveexec_b64 s[2:3], s[8:9]
	v_mov_b32_e32 v3, s92
	v_mov_b64_e32 v[4:5], s[18:19]
	ds_write_b64 v3, v[4:5] offset:17072
	s_or_b64 exec, exec, s[2:3]
	v_cmp_eq_u32_e64 s[18:19], s33, v2
	s_mov_b64 s[22:23], -1
	s_and_saveexec_b64 s[2:3], s[16:17]
	s_bcnt1_i32_b64 s16, s[20:21]
	v_mbcnt_lo_u32_b32 v2, s18, 0
	s_add_i32 s24, s24, s16
	v_mbcnt_hi_u32_b32 v2, s19, v2
	v_add_u32_e32 v2, s24, v2
	v_cmp_gt_i32_e64 s[16:17], s40, v2
	s_and_b64 s[16:17], s[18:19], s[16:17]
	s_orn2_b64 s[22:23], s[16:17], exec
	s_or_b64 exec, exec, s[2:3]
	v_cndmask_b32_e64 v2, 0, 1, s[22:23]
	v_cmp_ne_u32_e64 s[16:17], 0, v2
	s_and_saveexec_b64 s[2:3], s[8:9]
	v_mov_b32_e32 v2, s92
	v_mov_b64_e32 v[4:5], s[16:17]
	ds_write_b64 v2, v[4:5] offset:17080
	s_or_b64 exec, exec, s[2:3]
	v_mov_b32_e32 v4, 0x461c4001
	v_mov_b32_e32 v2, 0x461c4001
	s_and_saveexec_b64 s[2:3], s[26:27]
	s_cbranch_execz .LBB0_870
	ds_read_b32 v2, v191 offset:14848
	s_waitcnt lgkmcnt(0)
	v_max_f32_e32 v2, v2, v2
	v_max_f32_e32 v2, 0, v2
	v_add_u32_e32 v2, 1, v2

; __device__ __forceinline__ void a_unit(const ACtx& X, int b, int t0, float* ldsw, int lane) {
;     ...
;         for (int i = 0; i < 4; ++i) { const int j = lane + 64 * i; const float v = (j == 0 || j == cur || j == cur - 1) ? 1e4f : fmaxf(impL[qi * 256 + j], 0.f); key[i] = (j > cur) ? 0u : (__float_as_uint(v) + 1u); }
;         unsigned T = 0u;
;     ...
;             const unsigned cand = T | (1u << bit);
;             int cge = 0;
; #pragma unroll
;             for (int i = 0; i < 4; ++i) cge += __popcll(__ballot(key[i] >= cand));
;             if (cge >= cnt) T = cand;
;         }
;         int ngt = 0;
; #pragma unroll
;         for (int i = 0; i < 4; ++i) ngt += __popcll(__ballot(key[i] > T));
;         int need = cnt - ngt, base = 0;
; #pragma unroll
;         for (int i = 0; i < 4; ++i) {
;             const unsigned long long Me = __ballot(key[i] == T);
;             const int pos = base + (int)__builtin_amdgcn_mbcnt_hi((unsigned)(Me >> 32), __builtin_amdgcn_mbcnt_lo((unsigned)Me, 0u));
;             const bool sel = (key[i] > T) || (key[i] == T && pos < need);
;             const unsigned long long Ms = __ballot(sel);
;             if (lane == 0) { qbits[qi * 8 + 2 * i] = (unsigned)Ms; qbits[qi * 8 + 2 * i + 1] = (unsigned)(Ms >> 32); }
;             base += __popcll(Me);
;         }
.Ltk_cont_6:
	v_cmp_lt_u32_e64 s[16:17], s33, v5
	s_bcnt1_i32_b64 s2, s[16:17]
	v_cmp_lt_u32_e64 s[16:17], s33, v4
	s_bcnt1_i32_b64 s3, s[16:17]
	v_cmp_lt_u32_e64 s[16:17], s33, v3
	s_bcnt1_i32_b64 s36, s[16:17]
	v_cmp_lt_u32_e64 s[22:23], s33, v2
	s_add_i32 s2, s2, s3
	s_bcnt1_i32_b64 s22, s[22:23]
	s_add_i32 s2, s2, s36
	s_add_i32 s2, s2, s22
	v_cmp_ge_u32_e64 s[24:25], s33, v5
	v_cmp_ge_u32_e64 s[20:21], s33, v4
	v_cmp_ge_u32_e64 s[18:19], s33, v3
	v_cmp_ge_u32_e64 s[16:17], s33, v2
	s_sub_i32 s40, s39, s2
	v_cmp_eq_u32_e64 s[22:23], s33, v5
	s_mov_b64 s[36:37], -1
	s_and_saveexec_b64 s[2:3], s[24:25]
	v_mbcnt_lo_u32_b32 v5, s22, 0
	v_mbcnt_hi_u32_b32 v5, s23, v5
	v_cmp_gt_i32_e64 s[24:25], s40, v5
	s_and_b64 s[24:25], s[22:23], s[24:25]
	s_orn2_b64 s[36:37], s[24:25], exec
	s_or_b64 exec, exec, s[2:3]
	v_cndmask_b32_e64 v5, 0, 1, s[36:37]
	v_cmp_ne_u32_e64 s[24:25], 0, v5
	s_and_saveexec_b64 s[2:3], s[8:9]
	v_mov_b32_e32 v5, s92
	v_mov_b64_e32 v[6:7], s[24:25]
	ds_write_b64 v5, v[6:7] offset:17088
	s_or_b64 exec, exec, s[2:3]
	s_bcnt1_i32_b64 s36, s[22:23]
	v_cmp_eq_u32_e64 s[22:23], s33, v4
	s_mov_b64 s[24:25], -1
	s_and_saveexec_b64 s[2:3], s[20:21]
	v_mbcnt_lo_u32_b32 v4, s22, 0
	v_mbcnt_hi_u32_b32 v4, s23, v4
	v_add_u32_e32 v4, s36, v4
	v_cmp_gt_i32_e64 s[20:21], s40, v4
	s_and_b64 s[20:21], s[22:23], s[20:21]
	s_orn2_b64 s[24:25], s[20:21], exec
	s_or_b64 exec, exec, s[2:3]
	v_cndmask_b32_e64 v4, 0, 1, s[24:25]
	v_cmp_ne_u32_e64 s[20:21], 0, v4
	s_and_saveexec_b64 s[2:3], s[8:9]
	v_mov_b32_e32 v4, s92
	v_mov_b64_e32 v[6:7], s[20:21]
	ds_write_b64 v4, v[6:7] offset:17096
	s_or_b64 exec, exec, s[2:3]
	s_bcnt1_i32_b64 s24, s[22:23]
	s_add_i32 s24, s24, s36
	v_cmp_eq_u32_e64 s[20:21], s33, v3
	s_mov_b64 s[22:23], -1
	s_and_saveexec_b64 s[2:3], s[18:19]
	v_mbcnt_lo_u32_b32 v3, s20, 0
	v_mbcnt_hi_u32_b32 v3, s21, v3
	v_add_u32_e32 v3, s24, v3
	v_cmp_gt_i32_e64 s[18:19], s40, v3
	s_and_b64 s[18:19], s[20:21], s[18:19]
	s_orn2_b64 s[22:23], s[18:19], exec
	s_or_b64 exec, exec, s[2:3]
	v_cndmask_b32_e64 v3, 0, 1, s[22:23]
	v_cmp_ne_u32_e64 s[18:19], 0, v3
	s_and_saveexec_b64 s[2:3], s[8:9]
	v_mov_b32_e32 v3, s92
	v_mov_b64_e32 v[4:5], s[18:19]
	ds_write_b64 v3, v[4:5] offset:17104
	s_or_b64 exec, exec, s[2:3]
	v_cmp_eq_u32_e64 s[18:19], s33, v2
	s_mov_b64 s[22:23], -1
	s_and_saveexec_b64 s[2:3], s[16:17]
	s_bcnt1_i32_b64 s16, s[20:21]
	v_mbcnt_lo_u32_b32 v2, s18, 0
	s_add_i32 s24, s24, s16
	v_mbcnt_hi_u32_b32 v2, s19, v2
	v_add_u32_e32 v2, s24, v2
	v_cmp_gt_i32_e64 s[16:17], s40, v2
	s_and_b64 s[16:17], s[18:19], s[16:17]
	s_orn2_b64 s[22:23], s[16:17], exec
	s_or_b64 exec, exec, s[2:3]
	v_cndmask_b32_e64 v2, 0, 1, s[22:23]
	v_cmp_ne_u32_e64 s[16:17], 0, v2
	s_and_saveexec_b64 s[2:3], s[8:9]
	v_mov_b32_e32 v2, s92
	v_mov_b64_e32 v[4:5], s[16:17]
	ds_write_b64 v2, v[4:5] offset:17112
	s_or_b64 exec, exec, s[2:3]
	v_mov_b32_e32 v4, 0x461c4001
	v_mov_b32_e32 v2, 0x461c4001
	s_and_saveexec_b64 s[2:3], s[26:27]
	s_cbranch_execz .LBB0_896
	ds_read_b32 v2, v191 offset:15872
	s_waitcnt lgkmcnt(0)
	v_max_f32_e32 v2, v2, v2
	v_max_f32_e32 v2, 0, v2
	v_add_u32_e32 v2, 1, v2

; #define LDS_WAIT() asm volatile("s_waitcnt lgkmcnt(0)" ::: "memory")
; __device__ __forceinline__ void a_unit(const ACtx& X, int b, int t0, float* ldsw, int lane) {
;     ...
;         unsigned T = 0u;
;     ...
;             const unsigned cand = T | (1u << bit);
;             int cge = 0;
; #pragma unroll
;             for (int i = 0; i < 4; ++i) cge += __popcll(__ballot(key[i] >= cand));
;             if (cge >= cnt) T = cand;
;         }
;         int ngt = 0;
; #pragma unroll
;         for (int i = 0; i < 4; ++i) ngt += __popcll(__ballot(key[i] > T));
;         int need = cnt - ngt, base = 0;
; #pragma unroll
;         for (int i = 0; i < 4; ++i) {
;             const unsigned long long Me = __ballot(key[i] == T);
;             const int pos = base + (int)__builtin_amdgcn_mbcnt_hi((unsigned)(Me >> 32), __builtin_amdgcn_mbcnt_lo((unsigned)Me, 0u));
;             const bool sel = (key[i] > T) || (key[i] == T && pos < need);
;             const unsigned long long Ms = __ballot(sel);
;             if (lane == 0) { qbits[qi * 8 + 2 * i] = (unsigned)Ms; qbits[qi * 8 + 2 * i + 1] = (unsigned)(Ms >> 32); }
;             base += __popcll(Me);
;         }
;     }
;     LDS_WAIT(); __builtin_amdgcn_wave_barrier();
;     {
;         int nun = 0;
; #pragma unroll
;         for (int i = 0; i < 4; ++i) {
;             const int j = lane + 64 * i, w = j >> 5; unsigned u = 0u;
; #pragma unroll
;             for (int q = 0; q < 8; ++q) u |= ((qbits[q * 8 + w] >> (j & 31)) & 1u) << q;
;             const bool pr = u != 0u;
;             const unsigned long long Mb = __ballot(pr);
;             const int pos = nun + (int)__builtin_amdgcn_mbcnt_hi((unsigned)(Mb >> 32), __builtin_amdgcn_mbcnt_lo((unsigned)Mb, 0u));
;             if (pr) ulist[pos] = j | (int)(u << 8);
;             nun += __popcll(Mb);
.LBB0_902:
	s_or_b64 exec, exec, s[2:3]
	s_mov_b32 s20, 0
	v_cndmask_b32_e64 v3, v3, 0, vcc
	v_cndmask_b32_e64 v4, v4, 0, s[10:11]
	v_cndmask_b32_e64 v5, v2, 0, s[12:13]
	v_cndmask_b32_e64 v2, v6, 0, s[14:15]
	s_mov_b32 s2, 30
	s_add_i32 s100, s38, 1
.LBB0_903:
	s_lshl_b32 s3, 1, s2
	s_or_b32 s3, s3, s20
	v_cmp_le_u32_e32 vcc, s3, v5
	s_bcnt1_i32_b64 s10, vcc
	v_cmp_le_u32_e32 vcc, s3, v4
	s_bcnt1_i32_b64 s11, vcc
	v_cmp_le_u32_e32 vcc, s3, v3
	s_add_i32 s10, s11, s10
	s_bcnt1_i32_b64 s11, vcc
	v_cmp_le_u32_e32 vcc, s3, v2
	s_add_i32 s10, s10, s11
	s_bcnt1_i32_b64 s11, vcc
	s_add_i32 s10, s10, s11
	s_cmp_eq_u32 s10, s100
	s_cbranch_scc1 .Ltk_exit_7
	s_cmp_gt_u32 s10, s38
	s_cselect_b32 s20, s3, s20
	s_add_i32 s2, s2, -1
	s_cmp_lg_u32 s2, -1
	s_cbranch_scc1 .LBB0_903
.Ltk_cont_7:
	v_cmp_lt_u32_e32 vcc, s20, v5
	s_bcnt1_i32_b64 s2, vcc
	v_cmp_lt_u32_e32 vcc, s20, v4
	s_bcnt1_i32_b64 s3, vcc
	v_cmp_lt_u32_e32 vcc, s20, v3
	s_bcnt1_i32_b64 s18, vcc
	v_cmp_lt_u32_e64 s[14:15], s20, v2
	s_add_i32 s2, s2, s3
	s_bcnt1_i32_b64 s14, s[14:15]
	s_add_i32 s2, s2, s18
	s_add_i32 s2, s2, s14
	v_cmp_ge_u32_e64 s[16:17], s20, v5
	v_cmp_ge_u32_e64 s[12:13], s20, v4
	v_cmp_ge_u32_e64 s[10:11], s20, v3
	v_cmp_ge_u32_e32 vcc, s20, v2
	s_sub_i32 s21, s39, s2
	v_cmp_eq_u32_e64 s[14:15], s20, v5
	s_mov_b64 s[18:19], -1
	s_and_saveexec_b64 s[2:3], s[16:17]
	v_mbcnt_lo_u32_b32 v5, s14, 0
	v_mbcnt_hi_u32_b32 v5, s15, v5
	v_cmp_gt_i32_e64 s[16:17], s21, v5
	s_and_b64 s[16:17], s[14:15], s[16:17]
	s_orn2_b64 s[18:19], s[16:17], exec
	s_or_b64 exec, exec, s[2:3]
	v_cndmask_b32_e64 v5, 0, 1, s[18:19]
	v_cmp_ne_u32_e64 s[16:17], 0, v5
	s_and_saveexec_b64 s[2:3], s[8:9]
	v_mov_b32_e32 v5, s92
	v_mov_b64_e32 v[6:7], s[16:17]
	ds_write_b64 v5, v[6:7] offset:17120
	s_or_b64 exec, exec, s[2:3]
	s_bcnt1_i32_b64 s18, s[14:15]
	v_cmp_eq_u32_e64 s[14:15], s20, v4
	s_mov_b64 s[16:17], -1
	s_and_saveexec_b64 s[2:3], s[12:13]
	v_mbcnt_lo_u32_b32 v4, s14, 0
	v_mbcnt_hi_u32_b32 v4, s15, v4
	v_add_u32_e32 v4, s18, v4
	v_cmp_gt_i32_e64 s[12:13], s21, v4
	s_and_b64 s[12:13], s[14:15], s[12:13]
	s_orn2_b64 s[16:17], s[12:13], exec
	s_or_b64 exec, exec, s[2:3]
	v_cndmask_b32_e64 v4, 0, 1, s[16:17]
	v_cmp_ne_u32_e64 s[12:13], 0, v4
	s_and_saveexec_b64 s[2:3], s[8:9]
	v_mov_b32_e32 v4, s92
	v_mov_b64_e32 v[6:7], s[12:13]
	ds_write_b64 v4, v[6:7] offset:17128
	s_or_b64 exec, exec, s[2:3]
	s_bcnt1_i32_b64 s16, s[14:15]
	s_add_i32 s16, s16, s18
	v_cmp_eq_u32_e64 s[12:13], s20, v3
	s_mov_b64 s[14:15], -1
	s_and_saveexec_b64 s[2:3], s[10:11]
	v_mbcnt_lo_u32_b32 v3, s12, 0
	v_mbcnt_hi_u32_b32 v3, s13, v3
	v_add_u32_e32 v3, s16, v3
	v_cmp_gt_i32_e64 s[10:11], s21, v3
	s_and_b64 s[10:11], s[12:13], s[10:11]
	s_orn2_b64 s[14:15], s[10:11], exec
	s_or_b64 exec, exec, s[2:3]
	v_cndmask_b32_e64 v3, 0, 1, s[14:15]
	v_cmp_ne_u32_e64 s[10:11], 0, v3
	s_and_saveexec_b64 s[2:3], s[8:9]
	v_mov_b32_e32 v3, s92
	v_mov_b64_e32 v[4:5], s[10:11]
	ds_write_b64 v3, v[4:5] offset:17136
	s_or_b64 exec, exec, s[2:3]
	v_cmp_eq_u32_e64 s[10:11], s20, v2
	s_mov_b64 s[14:15], -1
	s_and_saveexec_b64 s[2:3], vcc
	s_bcnt1_i32_b64 s12, s[12:13]
	v_mbcnt_lo_u32_b32 v2, s10, 0
	s_add_i32 s16, s16, s12
	v_mbcnt_hi_u32_b32 v2, s11, v2
	v_add_u32_e32 v2, s16, v2
	v_cmp_gt_i32_e32 vcc, s21, v2
	s_and_b64 s[10:11], s[10:11], vcc
	s_orn2_b64 s[14:15], s[10:11], exec
	s_or_b64 exec, exec, s[2:3]
	v_cndmask_b32_e64 v2, 0, 1, s[14:15]
	v_cmp_ne_u32_e64 s[10:11], 0, v2
	s_and_saveexec_b64 s[2:3], s[8:9]
	v_mov_b32_e32 v2, s92
	v_mov_b64_e32 v[4:5], s[10:11]
	ds_write_b64 v2, v[4:5] offset:17144
	s_or_b64 exec, exec, s[2:3]
	v_add_u32_e32 v4, 0x4000, v209
	s_waitcnt lgkmcnt(0)
	ds_read2_b32 v[2:3], v4 offset0:128 offset1:136
	s_waitcnt lgkmcnt(0)
	v_lshrrev_b32_e32 v3, v208, v3
	v_bfe_u32 v2, v2, v208, 1
	v_lshlrev_b32_e32 v3, 1, v3
	v_and_or_b32 v5, v3, 2, v2
	ds_read2_b32 v[2:3], v4 offset0:144 offset1:152
	s_waitcnt lgkmcnt(0)
	v_lshrrev_b32_e32 v2, v208, v2
	v_lshrrev_b32_e32 v3, v208, v3
	v_lshlrev_b32_e32 v2, 2, v2
	v_lshlrev_b32_e32 v3, 3, v3
	v_and_b32_e32 v2, 4, v2
	v_and_b32_e32 v3, 8, v3
	v_or3_b32 v5, v5, v2, v3
	ds_read2_b32 v[2:3], v4 offset0:160 offset1:168
	s_waitcnt lgkmcnt(0)
	v_lshrrev_b32_e32 v2, v208, v2
	v_lshrrev_b32_e32 v3, v208, v3
	v_lshlrev_b32_e32 v2, 4, v2
	v_lshlrev_b32_e32 v3, 5, v3
	v_and_b32_e32 v2, 16, v2
	v_and_b32_e32 v3, 32, v3
	v_or3_b32 v5, v5, v2, v3
	ds_read2_b32 v[2:3], v4 offset0:176 offset1:184
	s_waitcnt lgkmcnt(0)
	v_lshrrev_b32_e32 v2, v208, v2
	v_lshrrev_b32_e32 v3, v208, v3
	v_lshlrev_b32_e32 v2, 6, v2
	v_lshlrev_b32_e32 v3, 7, v3
	v_and_b32_e32 v2, 64, v2
	v_and_b32_e32 v3, 0x80, v3
	v_or3_b32 v2, v5, v2, v3
	v_cmp_ne_u32_e32 vcc, 0, v2
	s_and_saveexec_b64 s[2:3], vcc
	s_nop 0
	v_mbcnt_lo_u32_b32 v3, vcc_lo, 0
	v_mbcnt_hi_u32_b32 v3, vcc_hi, v3
	v_lshl_or_b32 v2, v2, 8, v167
	v_lshl_add_u32 v3, v3, 2, s92
	ds_write_b32 v3, v2 offset:17152
	s_or_b64 exec, exec, s[2:3]
	v_add_u32_e32 v4, 0x4000, v210
	ds_read2_b32 v[2:3], v4 offset0:128 offset1:136
	s_bcnt1_i32_b64 s10, vcc
	s_waitcnt lgkmcnt(0)
	v_lshrrev_b32_e32 v3, v208, v3
	v_bfe_u32 v2, v2, v208, 1
	v_lshlrev_b32_e32 v3, 1, v3
	v_and_or_b32 v5, v3, 2, v2
	ds_read2_b32 v[2:3], v4 offset0:144 offset1:152
	s_waitcnt lgkmcnt(0)
	v_lshrrev_b32_e32 v2, v208, v2
	v_lshrrev_b32_e32 v3, v208, v3
	v_lshlrev_b32_e32 v2, 2, v2
	v_lshlrev_b32_e32 v3, 3, v3
	v_and_b32_e32 v2, 4, v2
	v_and_b32_e32 v3, 8, v3
	v_or3_b32 v5, v5, v2, v3
	ds_read2_b32 v[2:3], v4 offset0:160 offset1:168
	s_waitcnt lgkmcnt(0)
	v_lshrrev_b32_e32 v2, v208, v2
	v_lshrrev_b32_e32 v3, v208, v3
	v_lshlrev_b32_e32 v2, 4, v2
	v_lshlrev_b32_e32 v3, 5, v3
	v_and_b32_e32 v2, 16, v2
	v_and_b32_e32 v3, 32, v3
	v_or3_b32 v5, v5, v2, v3
	ds_read2_b32 v[2:3], v4 offset0:176 offset1:184
	s_waitcnt lgkmcnt(0)
	v_lshrrev_b32_e32 v2, v208, v2
	v_lshrrev_b32_e32 v3, v208, v3
	v_lshlrev_b32_e32 v2, 6, v2
	v_lshlrev_b32_e32 v3, 7, v3
	v_and_b32_e32 v2, 64, v2
	v_and_b32_e32 v3, 0x80, v3
	v_or3_b32 v2, v5, v2, v3
	v_cmp_ne_u32_e32 vcc, 0, v2
	s_and_saveexec_b64 s[2:3], vcc
	s_cbranch_execz .LBB0_924
	v_mbcnt_lo_u32_b32 v3, vcc_lo, 0
	s_lshl_b32 s11, s10, 2
	v_mbcnt_hi_u32_b32 v3, vcc_hi, v3
	s_add_i32 s11, s11, s92
	v_lshl_or_b32 v2, v2, 8, v195
	v_lshl_add_u32 v3, v3, 2, s11
	ds_write_b32 v3, v2 offset:17152

; __device__ __forceinline__ void a_unit(const ACtx& X, int b, int t0, float* ldsw, int lane) {
;     ...
;             const unsigned cand = T | (1u << bit);
;             int cge = 0;
; #pragma unroll
;             for (int i = 0; i < 4; ++i) cge += __popcll(__ballot(key[i] >= cand));
;             if (cge >= cnt) T = cand;
;         }
.Ltk_exit_0:
	s_mov_b32 s33, s3
	s_branch .Ltk_cont_0

; __device__ __forceinline__ void a_unit(const ACtx& X, int b, int t0, float* ldsw, int lane) {
;     ...
;             const unsigned cand = T | (1u << bit);
;             int cge = 0;
; #pragma unroll
;             for (int i = 0; i < 4; ++i) cge += __popcll(__ballot(key[i] >= cand));
;             if (cge >= cnt) T = cand;
;         }
.Ltk_exit_7:
	s_mov_b32 s20, s3
	s_branch .Ltk_cont_7
